# G1: conv output shuffle (46 v_mov) removed; section B hand-written per role reads the conv's natural register layout
# speedup vs baseline: 1.0058x; 1.0058x over previous
.LBB0_308:
	s_or_b64 exec, exec, s[44:45]
	v_lshrrev_b32_e32 v212, 4, v210
	s_waitcnt vmcnt(0) lgkmcnt(0)
	s_barrier
	s_and_saveexec_b64 s[8:9], s[38:39]
	s_cbranch_execz .LBB0_359
	v_readfirstlane_b32 s38, v188
	v_and_b32_e32 v44, 7, v212
	v_lshlrev_b32_e32 v70, 5, v44
	v_add_u32_e32 v70, 0x1f500, v70
	s_cmp_eq_u32 s38, 1
	s_cbranch_scc1 .Lg1b_k
	s_cmp_eq_u32 s38, 2
	s_cbranch_scc1 .Lg1b_v
	ds_read_b128 v[58:61], v70
	ds_read_b128 v[62:65], v70 offset:16
	v_and_b32_e32 v72, 3, v211
	v_lshrrev_b32_e32 v74, 2, v211
	v_lshlrev_b32_e32 v146, 1, v72
	v_and_b32_e32 v147, 1, v74
	v_xor_b32_e32 v146, v146, v147
	v_lshrrev_b32_e32 v76, 1, v44
	v_lshl_add_u32 v76, v76, 2, v74
	v_lshlrev_b32_e32 v76, 6, v76
	v_lshl_add_u32 v76, v72, 4, v76
	v_and_b32_e32 v147, 1, v44
	v_lshl_add_u32 v76, v147, 3, v76
	v_lshlrev_b32_e32 v76, 4, v76
	v_lshl_add_u32 v76, v146, 4, v76
	v_cvt_pk_bf16_f32 v50, v78, v79
	v_cvt_pk_bf16_f32 v51, v80, v81
	v_cvt_pk_bf16_f32 v52, v82, v83
	v_cvt_pk_bf16_f32 v53, v84, v85
	ds_write_b128 v76, v[50:53]
	v_cvt_pk_bf16_f32 v54, v102, v103
	v_cvt_pk_bf16_f32 v55, v104, v105
	v_cvt_pk_bf16_f32 v56, v106, v107
	v_cvt_pk_bf16_f32 v57, v108, v109
	v_xor_b32_e32 v147, 0x10, v76
	ds_write_b128 v147, v[54:57]
	v_cvt_pk_bf16_f32 v50, v90, v91
	v_cvt_pk_bf16_f32 v51, v86, v87
	v_cvt_pk_bf16_f32 v52, v88, v89
	v_cvt_pk_bf16_f32 v53, v92, v93
	v_xor_b32_e32 v146, 0x20, v76
	ds_write_b128 v146, v[50:53]
	v_cvt_pk_bf16_f32 v54, v114, v115
	v_cvt_pk_bf16_f32 v55, v116, v117
	v_cvt_pk_bf16_f32 v56, v126, v127
	v_cvt_pk_bf16_f32 v57, v128, v129
	v_xor_b32_e32 v147, 0x30, v76
	ds_write_b128 v147, v[54:57]
	v_cvt_pk_bf16_f32 v50, v96, v97
	v_cvt_pk_bf16_f32 v51, v94, v95
	v_cvt_pk_bf16_f32 v52, v98, v99
	v_cvt_pk_bf16_f32 v53, v100, v101
	v_xor_b32_e32 v146, 0x40, v76
	ds_write_b128 v146, v[50:53]
	v_cvt_pk_bf16_f32 v54, v138, v139
	v_cvt_pk_bf16_f32 v55, v140, v141
	v_cvt_pk_bf16_f32 v56, v154, v155
	v_cvt_pk_bf16_f32 v57, v130, v131
	v_xor_b32_e32 v147, 0x50, v76
	ds_write_b128 v147, v[54:57]
	v_cvt_pk_bf16_f32 v50, v156, v157
	v_cvt_pk_bf16_f32 v51, v136, v137
	v_cvt_pk_bf16_f32 v52, v112, v113
	v_cvt_pk_bf16_f32 v53, v110, v111
	v_xor_b32_e32 v146, 0x60, v76
	ds_write_b128 v146, v[50:53]
	v_cvt_pk_bf16_f32 v54, v71, v75
	v_cvt_pk_bf16_f32 v55, v77, v73
	v_cvt_pk_bf16_f32 v56, v46, v47
	v_cvt_pk_bf16_f32 v57, v48, v49
	v_xor_b32_e32 v147, 0x70, v76
	ds_write_b128 v147, v[54:57]
	v_mul_u32_u24_e32 v72, 0x880, v44
	v_lshl_add_u32 v72, v211, 4, v72
	v_add_u32_e32 v72, 0x10400, v72
	s_waitcnt lgkmcnt(8)
	v_pk_mul_f32 v[66:67], v[78:79], v[58:59] op_sel_hi:[1,0]
	v_pk_mul_f32 v[68:69], v[80:81], v[58:59] op_sel_hi:[1,0]
	v_pk_mul_f32 v[142:143], v[82:83], v[58:59] op_sel_hi:[1,0]
	v_pk_mul_f32 v[144:145], v[84:85], v[58:59] op_sel_hi:[1,0]
	v_cvt_pk_bf16_f32 v50, v66, v67
	v_cvt_pk_bf16_f32 v51, v68, v69
	v_cvt_pk_bf16_f32 v52, v142, v143
	v_cvt_pk_bf16_f32 v53, v144, v145
	ds_write_b128 v72, v[50:53]
	v_pk_mul_f32 v[66:67], v[102:103], v[58:59] op_sel:[0,1]
	v_pk_mul_f32 v[68:69], v[104:105], v[58:59] op_sel:[0,1]
	v_pk_mul_f32 v[142:143], v[106:107], v[58:59] op_sel:[0,1]
	v_pk_mul_f32 v[144:145], v[108:109], v[58:59] op_sel:[0,1]
	v_cvt_pk_bf16_f32 v54, v66, v67
	v_cvt_pk_bf16_f32 v55, v68, v69
	v_cvt_pk_bf16_f32 v56, v142, v143
	v_cvt_pk_bf16_f32 v57, v144, v145
	ds_write_b128 v72, v[54:57] offset:272
	v_pk_mul_f32 v[66:67], v[90:91], v[60:61] op_sel_hi:[1,0]
	v_pk_mul_f32 v[68:69], v[86:87], v[60:61] op_sel_hi:[1,0]
	v_pk_mul_f32 v[142:143], v[88:89], v[60:61] op_sel_hi:[1,0]
	v_pk_mul_f32 v[144:145], v[92:93], v[60:61] op_sel_hi:[1,0]
	v_cvt_pk_bf16_f32 v50, v66, v67
	v_cvt_pk_bf16_f32 v51, v68, v69
	v_cvt_pk_bf16_f32 v52, v142, v143
	v_cvt_pk_bf16_f32 v53, v144, v145
	ds_write_b128 v72, v[50:53] offset:544
	v_pk_mul_f32 v[66:67], v[114:115], v[60:61] op_sel:[0,1]
	v_pk_mul_f32 v[68:69], v[116:117], v[60:61] op_sel:[0,1]
	v_pk_mul_f32 v[142:143], v[126:127], v[60:61] op_sel:[0,1]
	v_pk_mul_f32 v[144:145], v[128:129], v[60:61] op_sel:[0,1]
	v_cvt_pk_bf16_f32 v54, v66, v67
	v_cvt_pk_bf16_f32 v55, v68, v69
	v_cvt_pk_bf16_f32 v56, v142, v143
	v_cvt_pk_bf16_f32 v57, v144, v145
	ds_write_b128 v72, v[54:57] offset:816
	v_pk_mul_f32 v[66:67], v[96:97], v[62:63] op_sel_hi:[1,0]
	v_pk_mul_f32 v[68:69], v[94:95], v[62:63] op_sel_hi:[1,0]
	v_pk_mul_f32 v[142:143], v[98:99], v[62:63] op_sel_hi:[1,0]
	v_pk_mul_f32 v[144:145], v[100:101], v[62:63] op_sel_hi:[1,0]
	v_cvt_pk_bf16_f32 v50, v66, v67
	v_cvt_pk_bf16_f32 v51, v68, v69
	v_cvt_pk_bf16_f32 v52, v142, v143
	v_cvt_pk_bf16_f32 v53, v144, v145
	ds_write_b128 v72, v[50:53] offset:1088
	v_pk_mul_f32 v[66:67], v[138:139], v[62:63] op_sel:[0,1]
	v_pk_mul_f32 v[68:69], v[140:141], v[62:63] op_sel:[0,1]
	v_pk_mul_f32 v[142:143], v[154:155], v[62:63] op_sel:[0,1]
	v_pk_mul_f32 v[144:145], v[130:131], v[62:63] op_sel:[0,1]
	v_cvt_pk_bf16_f32 v54, v66, v67
	v_cvt_pk_bf16_f32 v55, v68, v69
	v_cvt_pk_bf16_f32 v56, v142, v143
	v_cvt_pk_bf16_f32 v57, v144, v145
	ds_write_b128 v72, v[54:57] offset:1360
	v_pk_mul_f32 v[66:67], v[156:157], v[64:65] op_sel_hi:[1,0]
	v_pk_mul_f32 v[68:69], v[136:137], v[64:65] op_sel_hi:[1,0]
	v_pk_mul_f32 v[142:143], v[112:113], v[64:65] op_sel_hi:[1,0]
	v_pk_mul_f32 v[144:145], v[110:111], v[64:65] op_sel_hi:[1,0]
	v_cvt_pk_bf16_f32 v50, v66, v67
	v_cvt_pk_bf16_f32 v51, v68, v69
	v_cvt_pk_bf16_f32 v52, v142, v143
	v_cvt_pk_bf16_f32 v53, v144, v145
	ds_write_b128 v72, v[50:53] offset:1632
	v_mul_f32_e32 v66, v71, v65
	v_mul_f32_e32 v67, v75, v65
	v_mul_f32_e32 v68, v77, v65
	v_mul_f32_e32 v69, v73, v65
	v_pk_mul_f32 v[142:143], v[46:47], v[64:65] op_sel:[0,1]
	v_pk_mul_f32 v[144:145], v[48:49], v[64:65] op_sel:[0,1]
	v_cvt_pk_bf16_f32 v54, v66, v67
	v_cvt_pk_bf16_f32 v55, v68, v69
	v_cvt_pk_bf16_f32 v56, v142, v143
	v_cvt_pk_bf16_f32 v57, v144, v145
	ds_write_b128 v72, v[54:57] offset:1904
	s_branch .LBB0_359
.Lg1b_v:
	ds_read_b128 v[50:53], v70 offset:256
	ds_read_b128 v[54:57], v70 offset:272
	v_mul_u32_u24_e32 v72, 0x1080, v44
	v_lshl_add_u32 v72, v211, 4, v72
	v_add_u32_e32 v72, 0x8000, v72
	s_waitcnt lgkmcnt(0)
	v_pk_mul_f32 v[66:67], v[78:79], v[50:51] op_sel_hi:[1,0]
	v_pk_mul_f32 v[68:69], v[80:81], v[50:51] op_sel_hi:[1,0]
	v_pk_mul_f32 v[142:143], v[82:83], v[50:51] op_sel_hi:[1,0]
	v_pk_mul_f32 v[144:145], v[84:85], v[50:51] op_sel_hi:[1,0]
	v_cvt_pk_bf16_f32 v58, v66, v67
	v_cvt_pk_bf16_f32 v59, v68, v69
	v_cvt_pk_bf16_f32 v60, v142, v143
	v_cvt_pk_bf16_f32 v61, v144, v145
	ds_write_b128 v72, v[58:61]
	v_pk_mul_f32 v[66:67], v[102:103], v[50:51] op_sel:[0,1]
	v_pk_mul_f32 v[68:69], v[104:105], v[50:51] op_sel:[0,1]
	v_pk_mul_f32 v[142:143], v[106:107], v[50:51] op_sel:[0,1]
	v_pk_mul_f32 v[144:145], v[108:109], v[50:51] op_sel:[0,1]
	v_cvt_pk_bf16_f32 v62, v66, v67
	v_cvt_pk_bf16_f32 v63, v68, v69
	v_cvt_pk_bf16_f32 v64, v142, v143
	v_cvt_pk_bf16_f32 v65, v144, v145
	ds_write_b128 v72, v[62:65] offset:528
	v_pk_mul_f32 v[66:67], v[90:91], v[52:53] op_sel_hi:[1,0]
	v_pk_mul_f32 v[68:69], v[86:87], v[52:53] op_sel_hi:[1,0]
	v_pk_mul_f32 v[142:143], v[88:89], v[52:53] op_sel_hi:[1,0]
	v_pk_mul_f32 v[144:145], v[92:93], v[52:53] op_sel_hi:[1,0]
	v_cvt_pk_bf16_f32 v58, v66, v67
	v_cvt_pk_bf16_f32 v59, v68, v69
	v_cvt_pk_bf16_f32 v60, v142, v143
	v_cvt_pk_bf16_f32 v61, v144, v145
	ds_write_b128 v72, v[58:61] offset:1056
	v_pk_mul_f32 v[66:67], v[114:115], v[52:53] op_sel:[0,1]
	v_pk_mul_f32 v[68:69], v[116:117], v[52:53] op_sel:[0,1]
	v_pk_mul_f32 v[142:143], v[126:127], v[52:53] op_sel:[0,1]
	v_pk_mul_f32 v[144:145], v[128:129], v[52:53] op_sel:[0,1]
	v_cvt_pk_bf16_f32 v62, v66, v67
	v_cvt_pk_bf16_f32 v63, v68, v69
	v_cvt_pk_bf16_f32 v64, v142, v143
	v_cvt_pk_bf16_f32 v65, v144, v145
	ds_write_b128 v72, v[62:65] offset:1584
	v_pk_mul_f32 v[66:67], v[96:97], v[54:55] op_sel_hi:[1,0]
	v_pk_mul_f32 v[68:69], v[94:95], v[54:55] op_sel_hi:[1,0]
	v_pk_mul_f32 v[142:143], v[98:99], v[54:55] op_sel_hi:[1,0]
	v_pk_mul_f32 v[144:145], v[100:101], v[54:55] op_sel_hi:[1,0]
	v_cvt_pk_bf16_f32 v58, v66, v67
	v_cvt_pk_bf16_f32 v59, v68, v69
	v_cvt_pk_bf16_f32 v60, v142, v143
	v_cvt_pk_bf16_f32 v61, v144, v145
	ds_write_b128 v72, v[58:61] offset:2112
	v_pk_mul_f32 v[66:67], v[138:139], v[54:55] op_sel:[0,1]
	v_pk_mul_f32 v[68:69], v[140:141], v[54:55] op_sel:[0,1]
	v_pk_mul_f32 v[142:143], v[154:155], v[54:55] op_sel:[0,1]
	v_pk_mul_f32 v[144:145], v[130:131], v[54:55] op_sel:[0,1]
	v_cvt_pk_bf16_f32 v62, v66, v67
	v_cvt_pk_bf16_f32 v63, v68, v69
	v_cvt_pk_bf16_f32 v64, v142, v143
	v_cvt_pk_bf16_f32 v65, v144, v145
	ds_write_b128 v72, v[62:65] offset:2640
	v_pk_mul_f32 v[66:67], v[156:157], v[56:57] op_sel_hi:[1,0]
	v_pk_mul_f32 v[68:69], v[136:137], v[56:57] op_sel_hi:[1,0]
	v_pk_mul_f32 v[142:143], v[112:113], v[56:57] op_sel_hi:[1,0]
	v_pk_mul_f32 v[144:145], v[110:111], v[56:57] op_sel_hi:[1,0]
	v_cvt_pk_bf16_f32 v58, v66, v67
	v_cvt_pk_bf16_f32 v59, v68, v69
	v_cvt_pk_bf16_f32 v60, v142, v143
	v_cvt_pk_bf16_f32 v61, v144, v145
	ds_write_b128 v72, v[58:61] offset:3168
	v_mul_f32_e32 v66, v71, v57
	v_mul_f32_e32 v67, v75, v57
	v_mul_f32_e32 v68, v77, v57
	v_mul_f32_e32 v69, v73, v57
	v_pk_mul_f32 v[142:143], v[46:47], v[56:57] op_sel:[0,1]
	v_pk_mul_f32 v[144:145], v[48:49], v[56:57] op_sel:[0,1]
	v_cvt_pk_bf16_f32 v62, v66, v67
	v_cvt_pk_bf16_f32 v63, v68, v69
	v_cvt_pk_bf16_f32 v64, v142, v143
	v_cvt_pk_bf16_f32 v65, v144, v145
	ds_write_b128 v72, v[62:65] offset:3696
	s_branch .LBB0_359
.Lg1b_k:
	ds_read_b128 v[58:61], v70
	ds_read_b128 v[62:65], v70 offset:16
	ds_read_b128 v[50:53], v70 offset:256
	ds_read_b128 v[54:57], v70 offset:272
	ds_read_b128 v[118:121], v70 offset:512
	ds_read_b128 v[122:125], v70 offset:528
	v_and_b32_e32 v72, 3, v211
	v_lshrrev_b32_e32 v74, 2, v211
	v_lshlrev_b32_e32 v146, 1, v72
	v_and_b32_e32 v147, 1, v74
	v_xor_b32_e32 v146, v146, v147
	v_lshrrev_b32_e32 v76, 1, v44
	v_lshl_add_u32 v76, v76, 2, v74
	v_lshlrev_b32_e32 v76, 6, v76
	v_lshl_add_u32 v76, v72, 4, v76
	v_and_b32_e32 v147, 1, v44
	v_lshl_add_u32 v76, v147, 3, v76
	v_lshlrev_b32_e32 v76, 4, v76
	v_lshl_add_u32 v76, v146, 4, v76
	v_add_u32_e32 v76, 0x4000, v76
	v_cvt_pk_bf16_f32 v66, v78, v79
	v_cvt_pk_bf16_f32 v67, v80, v81
	v_cvt_pk_bf16_f32 v68, v82, v83
	v_cvt_pk_bf16_f32 v69, v84, v85
	ds_write_b128 v76, v[66:69]
	v_cvt_pk_bf16_f32 v142, v102, v103
	v_cvt_pk_bf16_f32 v143, v104, v105
	v_cvt_pk_bf16_f32 v144, v106, v107
	v_cvt_pk_bf16_f32 v145, v108, v109
	v_xor_b32_e32 v147, 0x10, v76
	ds_write_b128 v147, v[142:145]
	v_cvt_pk_bf16_f32 v66, v90, v91
	v_cvt_pk_bf16_f32 v67, v86, v87
	v_cvt_pk_bf16_f32 v68, v88, v89
	v_cvt_pk_bf16_f32 v69, v92, v93
	v_xor_b32_e32 v146, 0x20, v76
	ds_write_b128 v146, v[66:69]
	v_cvt_pk_bf16_f32 v142, v114, v115
	v_cvt_pk_bf16_f32 v143, v116, v117
	v_cvt_pk_bf16_f32 v144, v126, v127
	v_cvt_pk_bf16_f32 v145, v128, v129
	v_xor_b32_e32 v147, 0x30, v76
	ds_write_b128 v147, v[142:145]
	v_cvt_pk_bf16_f32 v66, v96, v97
	v_cvt_pk_bf16_f32 v67, v94, v95
	v_cvt_pk_bf16_f32 v68, v98, v99
	v_cvt_pk_bf16_f32 v69, v100, v101
	v_xor_b32_e32 v146, 0x40, v76
	ds_write_b128 v146, v[66:69]
	v_cvt_pk_bf16_f32 v142, v138, v139
	v_cvt_pk_bf16_f32 v143, v140, v141
	v_cvt_pk_bf16_f32 v144, v154, v155
	v_cvt_pk_bf16_f32 v145, v130, v131
	v_xor_b32_e32 v147, 0x50, v76
	ds_write_b128 v147, v[142:145]
	v_cvt_pk_bf16_f32 v66, v156, v157
	v_cvt_pk_bf16_f32 v67, v136, v137
	v_cvt_pk_bf16_f32 v68, v112, v113
	v_cvt_pk_bf16_f32 v69, v110, v111
	v_xor_b32_e32 v146, 0x60, v76
	ds_write_b128 v146, v[66:69]
	v_cvt_pk_bf16_f32 v142, v71, v75
	v_cvt_pk_bf16_f32 v143, v77, v73
	v_cvt_pk_bf16_f32 v144, v46, v47
	v_cvt_pk_bf16_f32 v145, v48, v49
	v_xor_b32_e32 v147, 0x70, v76
	ds_write_b128 v147, v[142:145]
	v_mul_u32_u24_e32 v72, 0x1080, v44
	v_lshl_add_u32 v72, v211, 4, v72
	v_add_u32_e32 v72, 0x8100, v72
	s_waitcnt lgkmcnt(8)
	v_pk_mul_f32 v[50:51], v[50:51], v[58:59]
	v_pk_mul_f32 v[52:53], v[52:53], v[60:61]
	v_pk_mul_f32 v[54:55], v[54:55], v[62:63]
	v_pk_mul_f32 v[56:57], v[56:57], v[64:65]
	v_and_b32_e32 v74, 7, v211
	v_xor_b32_e32 v74, v74, v44
	v_mul_u32_u24_e32 v76, 0x480, v211
	v_lshl_add_u32 v74, v74, 4, v76
	v_add_u32_e32 v74, 0x14800, v74
	v_pk_mul_f32 v[66:67], v[78:79], v[50:51] op_sel_hi:[1,0]
	v_pk_mul_f32 v[68:69], v[80:81], v[50:51] op_sel_hi:[1,0]
	v_pk_mul_f32 v[142:143], v[82:83], v[50:51] op_sel_hi:[1,0]
	v_pk_mul_f32 v[144:145], v[84:85], v[50:51] op_sel_hi:[1,0]
	v_cvt_pk_bf16_f32 v58, v66, v67
	v_cvt_pk_bf16_f32 v59, v68, v69
	v_cvt_pk_bf16_f32 v60, v142, v143
	v_cvt_pk_bf16_f32 v61, v144, v145
	ds_write_b128 v72, v[58:61]
	v_pk_mul_f32 v[66:67], v[102:103], v[50:51] op_sel:[0,1]
	v_pk_mul_f32 v[68:69], v[104:105], v[50:51] op_sel:[0,1]
	v_pk_mul_f32 v[142:143], v[106:107], v[50:51] op_sel:[0,1]
	v_pk_mul_f32 v[144:145], v[108:109], v[50:51] op_sel:[0,1]
	v_cvt_pk_bf16_f32 v62, v66, v67
	v_cvt_pk_bf16_f32 v63, v68, v69
	v_cvt_pk_bf16_f32 v64, v142, v143
	v_cvt_pk_bf16_f32 v65, v144, v145
	ds_write_b128 v72, v[62:65] offset:528
	v_pk_mul_f32 v[66:67], v[90:91], v[52:53] op_sel_hi:[1,0]
	v_pk_mul_f32 v[68:69], v[86:87], v[52:53] op_sel_hi:[1,0]
	v_pk_mul_f32 v[142:143], v[88:89], v[52:53] op_sel_hi:[1,0]
	v_pk_mul_f32 v[144:145], v[92:93], v[52:53] op_sel_hi:[1,0]
	v_cvt_pk_bf16_f32 v58, v66, v67
	v_cvt_pk_bf16_f32 v59, v68, v69
	v_cvt_pk_bf16_f32 v60, v142, v143
	v_cvt_pk_bf16_f32 v61, v144, v145
	ds_write_b128 v72, v[58:61] offset:1056
	v_pk_mul_f32 v[66:67], v[114:115], v[52:53] op_sel:[0,1]
	v_pk_mul_f32 v[68:69], v[116:117], v[52:53] op_sel:[0,1]
	v_pk_mul_f32 v[142:143], v[126:127], v[52:53] op_sel:[0,1]
	v_pk_mul_f32 v[144:145], v[128:129], v[52:53] op_sel:[0,1]
	v_cvt_pk_bf16_f32 v62, v66, v67
	v_cvt_pk_bf16_f32 v63, v68, v69
	v_cvt_pk_bf16_f32 v64, v142, v143
	v_cvt_pk_bf16_f32 v65, v144, v145
	ds_write_b128 v72, v[62:65] offset:1584
	v_pk_mul_f32 v[66:67], v[96:97], v[54:55] op_sel_hi:[1,0]
	v_pk_mul_f32 v[68:69], v[94:95], v[54:55] op_sel_hi:[1,0]
	v_pk_mul_f32 v[142:143], v[98:99], v[54:55] op_sel_hi:[1,0]
	v_pk_mul_f32 v[144:145], v[100:101], v[54:55] op_sel_hi:[1,0]
	v_cvt_pk_bf16_f32 v58, v66, v67
	v_cvt_pk_bf16_f32 v59, v68, v69
	v_cvt_pk_bf16_f32 v60, v142, v143
	v_cvt_pk_bf16_f32 v61, v144, v145
	ds_write_b128 v72, v[58:61] offset:2112
	v_pk_mul_f32 v[66:67], v[138:139], v[54:55] op_sel:[0,1]
	v_pk_mul_f32 v[68:69], v[140:141], v[54:55] op_sel:[0,1]
	v_pk_mul_f32 v[142:143], v[154:155], v[54:55] op_sel:[0,1]
	v_pk_mul_f32 v[144:145], v[130:131], v[54:55] op_sel:[0,1]
	v_cvt_pk_bf16_f32 v62, v66, v67
	v_cvt_pk_bf16_f32 v63, v68, v69
	v_cvt_pk_bf16_f32 v64, v142, v143
	v_cvt_pk_bf16_f32 v65, v144, v145
	ds_write_b128 v72, v[62:65] offset:2640
	v_pk_mul_f32 v[66:67], v[156:157], v[56:57] op_sel_hi:[1,0]
	v_pk_mul_f32 v[68:69], v[136:137], v[56:57] op_sel_hi:[1,0]
	v_pk_mul_f32 v[142:143], v[112:113], v[56:57] op_sel_hi:[1,0]
	v_pk_mul_f32 v[144:145], v[110:111], v[56:57] op_sel_hi:[1,0]
	v_cvt_pk_bf16_f32 v58, v66, v67
	v_cvt_pk_bf16_f32 v59, v68, v69
	v_cvt_pk_bf16_f32 v60, v142, v143
	v_cvt_pk_bf16_f32 v61, v144, v145
	ds_write_b128 v72, v[58:61] offset:3168
	v_mul_f32_e32 v66, v71, v57
	v_mul_f32_e32 v67, v75, v57
	v_mul_f32_e32 v68, v77, v57
	v_mul_f32_e32 v69, v73, v57
	v_pk_mul_f32 v[142:143], v[46:47], v[56:57] op_sel:[0,1]
	v_pk_mul_f32 v[144:145], v[48:49], v[56:57] op_sel:[0,1]
	v_cvt_pk_bf16_f32 v62, v66, v67
	v_cvt_pk_bf16_f32 v63, v68, v69
	v_cvt_pk_bf16_f32 v64, v142, v143
	v_cvt_pk_bf16_f32 v65, v144, v145
	ds_write_b128 v72, v[62:65] offset:3696
	v_mul_f32_e32 v66, v78, v118
	v_mul_f32_e32 v67, v102, v119
	v_mul_f32_e32 v68, v90, v120
	v_mul_f32_e32 v69, v114, v121
	v_mul_f32_e32 v142, v96, v122
	v_mul_f32_e32 v143, v138, v123
	v_mul_f32_e32 v144, v156, v124
	v_mul_f32_e32 v145, v71, v125
	v_cvt_pk_bf16_f32 v58, v66, v67
	v_cvt_pk_bf16_f32 v59, v68, v69
	v_cvt_pk_bf16_f32 v60, v142, v143
	v_cvt_pk_bf16_f32 v61, v144, v145
	ds_write_b128 v74, v[58:61]
	v_mul_f32_e32 v66, v79, v118
	v_mul_f32_e32 v67, v103, v119
	v_mul_f32_e32 v68, v91, v120
	v_mul_f32_e32 v69, v115, v121
	v_mul_f32_e32 v142, v97, v122
	v_mul_f32_e32 v143, v139, v123
	v_mul_f32_e32 v144, v157, v124
	v_mul_f32_e32 v145, v75, v125
	v_cvt_pk_bf16_f32 v62, v66, v67
	v_cvt_pk_bf16_f32 v63, v68, v69
	v_cvt_pk_bf16_f32 v64, v142, v143
	v_cvt_pk_bf16_f32 v65, v144, v145
	ds_write_b128 v74, v[62:65] offset:144
	v_mul_f32_e32 v66, v80, v118
	v_mul_f32_e32 v67, v104, v119
	v_mul_f32_e32 v68, v86, v120
	v_mul_f32_e32 v69, v116, v121
	v_mul_f32_e32 v142, v94, v122
	v_mul_f32_e32 v143, v140, v123
	v_mul_f32_e32 v144, v136, v124
	v_mul_f32_e32 v145, v77, v125
	v_cvt_pk_bf16_f32 v58, v66, v67
	v_cvt_pk_bf16_f32 v59, v68, v69
	v_cvt_pk_bf16_f32 v60, v142, v143
	v_cvt_pk_bf16_f32 v61, v144, v145
	ds_write_b128 v74, v[58:61] offset:288
	v_mul_f32_e32 v66, v81, v118
	v_mul_f32_e32 v67, v105, v119
	v_mul_f32_e32 v68, v87, v120
	v_mul_f32_e32 v69, v117, v121
	v_mul_f32_e32 v142, v95, v122
	v_mul_f32_e32 v143, v141, v123
	v_mul_f32_e32 v144, v137, v124
	v_mul_f32_e32 v145, v73, v125
	v_cvt_pk_bf16_f32 v62, v66, v67
	v_cvt_pk_bf16_f32 v63, v68, v69
	v_cvt_pk_bf16_f32 v64, v142, v143
	v_cvt_pk_bf16_f32 v65, v144, v145
	ds_write_b128 v74, v[62:65] offset:432
	v_mul_f32_e32 v66, v82, v118
	v_mul_f32_e32 v67, v106, v119
	v_mul_f32_e32 v68, v88, v120
	v_mul_f32_e32 v69, v126, v121
	v_mul_f32_e32 v142, v98, v122
	v_mul_f32_e32 v143, v154, v123
	v_mul_f32_e32 v144, v112, v124
	v_mul_f32_e32 v145, v46, v125
	v_cvt_pk_bf16_f32 v58, v66, v67
	v_cvt_pk_bf16_f32 v59, v68, v69
	v_cvt_pk_bf16_f32 v60, v142, v143
	v_cvt_pk_bf16_f32 v61, v144, v145
	ds_write_b128 v74, v[58:61] offset:576
	v_mul_f32_e32 v66, v83, v118
	v_mul_f32_e32 v67, v107, v119
	v_mul_f32_e32 v68, v89, v120
	v_mul_f32_e32 v69, v127, v121
	v_mul_f32_e32 v142, v99, v122
	v_mul_f32_e32 v143, v155, v123
	v_mul_f32_e32 v144, v113, v124
	v_mul_f32_e32 v145, v47, v125
	v_cvt_pk_bf16_f32 v62, v66, v67
	v_cvt_pk_bf16_f32 v63, v68, v69
	v_cvt_pk_bf16_f32 v64, v142, v143
	v_cvt_pk_bf16_f32 v65, v144, v145
	ds_write_b128 v74, v[62:65] offset:720
	v_mul_f32_e32 v66, v84, v118
	v_mul_f32_e32 v67, v108, v119
	v_mul_f32_e32 v68, v92, v120
	v_mul_f32_e32 v69, v128, v121
	v_mul_f32_e32 v142, v100, v122
	v_mul_f32_e32 v143, v130, v123
	v_mul_f32_e32 v144, v110, v124
	v_mul_f32_e32 v145, v48, v125
	v_cvt_pk_bf16_f32 v58, v66, v67
	v_cvt_pk_bf16_f32 v59, v68, v69
	v_cvt_pk_bf16_f32 v60, v142, v143
	v_cvt_pk_bf16_f32 v61, v144, v145
	ds_write_b128 v74, v[58:61] offset:864
	v_mul_f32_e32 v66, v85, v118
	v_mul_f32_e32 v67, v109, v119
	v_mul_f32_e32 v68, v93, v120
	v_mul_f32_e32 v69, v129, v121
	v_mul_f32_e32 v142, v101, v122
	v_mul_f32_e32 v143, v131, v123
	v_mul_f32_e32 v144, v111, v124
	v_mul_f32_e32 v145, v49, v125
	v_cvt_pk_bf16_f32 v62, v66, v67
	v_cvt_pk_bf16_f32 v63, v68, v69
	v_cvt_pk_bf16_f32 v64, v142, v143
	v_cvt_pk_bf16_f32 v65, v144, v145
	ds_write_b128 v74, v[62:65] offset:1008
